# inproj1 as well: each block's 6 tile pairs rotated so the lightest-epilogue kind (pc / val) is processed last
# baseline (speedup 1.0000x reference)
.LBB0_427:
	s_or_b64 exec, exec, s[0:1]
	s_cmpk_gt_i32 s2, 0x17ff
	s_waitcnt lgkmcnt(0)
	s_barrier
	s_cbranch_scc1 .LBB0_448
	v_xor_b32_e32 v0, v128, v131
	v_and_b32_e32 v64, 0x3f800, v149
	v_mov_b32_e32 v65, 0
	v_lshlrev_b32_e32 v0, 4, v0
	v_and_b32_e32 v0, 0x70, v0
	v_mov_b32_e32 v1, v65
	v_lshl_add_u64 v[2:3], s[50:51], 0, v[64:65]
	v_lshl_add_u64 v[66:67], v[2:3], 0, v[0:1]
	v_and_b32_e32 v0, 0x1e0, v153
	v_or_b32_e32 v1, v0, v138
	v_bitop3_b32 v2, v128, v139, 3 bitop3:0x6c
	v_lshlrev_b32_e32 v161, 7, v1
	v_lshlrev_b32_e32 v1, 13, v135
	v_lshlrev_b32_e32 v160, 4, v2
	v_lshl_add_u32 v2, v134, 3, v138
	v_lshl_or_b32 v3, v134, 11, v1
	v_lshlrev_b32_e32 v5, 5, v138
	v_or3_b32 v163, v1, v137, v5
	v_lshl_or_b32 v164, v2, 2, v3
	v_add_u32_e32 v5, 0x60, v2
	v_add_u32_e32 v2, 0x70, v2
	v_and_b32_e32 v5, 0x7f, v5
	v_and_b32_e32 v2, 0x7f, v2
	v_lshl_or_b32 v165, v5, 2, v3
	v_lshl_or_b32 v166, v2, 2, v3
	v_add_u32_e32 v3, 8, v133
	v_and_b32_e32 v3, 0x78, v3
	v_lshlrev_b32_e32 v2, 9, v136
	v_lshlrev_b32_e32 v3, 2, v3
	v_or3_b32 v168, v1, v2, v3
	v_add_u32_e32 v3, 16, v133
	v_and_b32_e32 v3, 0x78, v3
	v_lshlrev_b32_e32 v2, 9, v132
	v_lshlrev_b32_e32 v3, 2, v3
	v_or3_b32 v170, v1, v2, v3
	v_add_u32_e32 v3, 24, v133
	v_and_b32_e32 v3, 0x78, v3
	s_add_u32 s47, s50, 0x1a00000
	v_lshlrev_b32_e32 v4, 5, v135
	v_lshlrev_b32_e32 v2, 9, v130
	v_lshlrev_b32_e32 v3, 2, v3
	s_addc_u32 s53, s51, 0
	s_mov_b64 s[0:1], 0x3a00000
	v_and_or_b32 v0, v154, 12, v0
	v_or3_b32 v172, v1, v2, v3
	v_or_b32_e32 v1, 16, v4
	v_add_u32_e32 v5, 0x100, v131
	v_add_u32_e32 v6, 0x200, v131
	v_add_u32_e32 v7, 0x300, v131
	v_add_u32_e32 v8, 0x500, v131
	v_add_u32_e32 v9, 0x600, v131
	v_add_u32_e32 v10, 0x700, v131
	s_add_u32 s6, s50, 0x1200000
	v_lshl_add_u64 v[68:69], v[66:67], 0, s[0:1]
	v_or_b32_e32 v174, v1, v134
	v_or_b32_e32 v175, v136, v1
	v_or_b32_e32 v176, v132, v1
	v_or_b32_e32 v177, v130, v1
	v_and_b32_e32 v1, 24, v153
	s_movk_i32 s0, 0x3c0
	v_lshrrev_b32_e32 v178, 4, v5
	v_lshrrev_b32_e32 v179, 4, v6
	v_lshrrev_b32_e32 v180, 4, v7
	v_lshrrev_b32_e32 v182, 4, v8
	v_lshrrev_b32_e32 v183, 4, v9
	v_lshrrev_b32_e32 v184, 4, v10
	s_addc_u32 s7, s51, 0
	v_lshl_or_b32 v72, v0, 6, v138
	v_bitop3_b32 v0, v128, 7, v131 bitop3:0x48
	v_or_b32_e32 v167, v134, v4
	v_or_b32_e32 v169, v136, v4
	v_or_b32_e32 v171, v132, v4
	v_or_b32_e32 v173, v130, v4
	v_and_or_b32 v1, v131, s0, v1
	v_mul_u32_u24_e32 v2, 0x110, v138
	v_lshlrev_b32_e32 v3, 4, v138
	v_mul_u32_u24_e32 v4, 0x110, v128
	v_mul_u32_u24_e32 v5, 0x110, v178
	v_mul_u32_u24_e32 v6, 0x110, v179
	v_mul_u32_u24_e32 v7, 0x110, v180
	v_mul_u32_u24_e32 v8, 0x110, v182
	v_mul_u32_u24_e32 v9, 0x110, v183
	v_mul_u32_u24_e32 v10, 0x110, v184
	s_add_u32 s8, s50, 0x1600000
	v_lshl_or_b32 v64, v0, 4, v64
	v_lshlrev_b32_e32 v71, 7, v138
	v_lshlrev_b32_e32 v162, 4, v152
	v_lshlrev_b32_e32 v70, 3, v138
	v_or_b32_e32 v181, 64, v128
	s_addc_u32 s9, s51, 0
	v_mov_b32_e32 v73, v65
	v_lshl_add_u64 v[74:75], s[50:51], 0, v[64:65]
	s_mov_b64 s[10:11], 0x10000
	v_add_u32_e32 v185, 0x1000, v129
	s_mov_b64 s[12:13], 0x20000
	v_add_u32_e32 v186, 0x2000, v129
	s_mov_b64 s[14:15], 0x30000
	v_add_u32_e32 v187, 0x3000, v129
	v_or_b32_e32 v188, 0x4000, v129
	v_add_u32_e32 v189, 0x5000, v129
	v_add_u32_e32 v190, 0x6000, v129
	v_add_u32_e32 v191, 0x7000, v129
	s_mov_b64 s[18:19], 0x3a00080
	s_mov_b64 s[20:21], 0x3a10080
	s_mov_b64 s[22:23], 0x3a20080
	s_mov_b64 s[24:25], 0x3a30080
	s_mov_b64 s[26:27], 0x80
	s_mov_b64 s[28:29], 0x10080
	s_mov_b64 s[30:31], 0x20080
	s_mov_b64 s[34:35], 0x30080
	s_mov_b32 s39, 0
	v_lshlrev_b32_e32 v192, 2, v138
	s_brev_b32 s46, 60
	s_mov_b32 s52, 0x358637bd
	s_mov_b32 s60, 0x800000
	s_mov_b32 s61, 0x9a00000
	s_movk_i32 s62, 0x7fff
	s_mov_b32 s63, 0x7060302
	v_add_u32_e32 v193, v1, v2
	v_add_u32_e32 v194, v3, v4
	v_add_u32_e32 v195, v3, v5
	v_add_u32_e32 v196, v3, v6
	v_add_u32_e32 v197, v3, v7
	v_add_u32_e32 v198, v3, v8
	v_add_u32_e32 v199, v3, v9
	v_add_u32_e32 v200, v3, v10
	v_mbcnt_hi_u32_b32 v201, -1, v155
	v_mov_b32_e32 v202, 0x3db504f3
	s_mov_b32 s64, s2
	s_mov_b32 s89, 0
	s_mov_b32 s95, -1
	s_cmp_eq_u32 s3, 0x200
	s_cbranch_scc0 .LBB0_430
	s_and_b32 s91, s2, 7
	s_lshr_b32 s95, s2, 8
	s_lshl_b32 s95, s95, 1
	s_add_i32 s91, s91, s95
	s_sub_i32 s95, s91, 6
	s_cmp_ge_i32 s91, 6
	s_cselect_b32 s91, s95, s91
	s_mul_i32 s91, s91, 3
	s_lshr_b32 s91, 0x28944, s91
	s_and_b32 s91, s91, 7
	s_lshl_b32 s91, s91, 9
	s_add_i32 s64, s2, s91
	s_mov_b32 s95, s64
	s_branch .LBB0_430
.LBB0_429:
	s_xor_b32 s89, s89, 1
	s_cmp_lg_u32 s89, 0
	s_cbranch_scc1 .LBB0_430
	s_add_i32 s64, s64, s3
	s_cmp_lt_i32 s95, 0
	s_cbranch_scc1 .Lmy_ip1_lin
	s_cmpk_lt_i32 s64, 0xc00
	s_cbranch_scc1 .Lmy_ip1_nw
	s_sub_i32 s64, s64, 0xc00
.Lmy_ip1_nw:
	s_cmp_eq_u32 s64, s95
	s_cbranch_scc1 .LBB0_448
	s_branch .LBB0_430
.Lmy_ip1_lin:
	s_cmpk_lt_i32 s64, 0xc00
	s_cbranch_scc0 .LBB0_448
